# attention unit prologue: second K tile requested together with the first K/V tiles (one dependent memory round trip less per unit)
# baseline (speedup 1.0000x reference)
; #define LAS __attribute__((address_space(3)))
; DI void attn_phase(LAS unsigned char* lds, const int wid, const bf16_t* Q, const bf16_t* Kn, const bf16_t* Kr, const bf16_t* Vt, bf16_t* O, int G, int c) {
;     ...
;         const long L = (long)it * G + c; if (L >= 2048) break;
;         const int xcd = (int)(L & 7), idx = (int)(L >> 3), bh = (idx >> 5) * 8 + xcd, qb = idx & 31, b = bh >> 3, h = bh & 7;
;         const size_t tok0 = (size_t)b * SEQ;
;         const int q0 = qb * 256 + wid * 32;
;         bf16x8 qf[2][3];
; #pragma unroll
;         for (int qt = 0; qt < 2; ++qt) { const bf16_t* qp = Q + (tok0 + q0 + 16 * qt + r16) * 768 + h * 96 + 8 * qd;
; #pragma unroll
;           for (int ks = 0; ks < 3; ++ks) qf[qt][ks] = *(const bf16x8*)(qp + 32 * ks); }
;         f32x4 oacc[4][2], sa[4][2], sb[4][2];
;         f32x4 negm0 = {0.f, 0.f, 0.f, 0.f}, negm1 = {0.f, 0.f, 0.f, 0.f};
; #pragma unroll
;         for (int t4 = 0; t4 < 4; ++t4) { oacc[t4][0] = (f32x4){0.f, 0.f, 0.f, 0.f}; oacc[t4][1] = (f32x4){0.f, 0.f, 0.f, 0.f}; }
;         float l0 = 0.f, l1 = 0.f;
;         const int skey = tid >> 3, sch = tid & 7;
;         const int rkey = (tid & 255) >> 2, rch = tid & 3;
;         const bf16_t* gkn = Kn + (tok0 + skey) * 512 + h * 64 + sch * 8;
;         const bf16_t* gkr = Kr + (tok0 + rkey) * 32 + rch * 8;
;         const bf16_t* gvt = Vt + (size_t)(h * 64 + skey) * T + tok0 + sch * 8;
;         const unsigned lkn = skey * KS_STRIDE + sch * 16, lkr = rkey * KS_STRIDE + 128 + rch * 16, lvt = VOFF + skey * VS_STRIDE + (sch >> 2) * 64 + ((sch & 1) * 4 + ((sch >> 1) & 1)) * 8;
;         u32x4 rkn = *(const u32x4*)gkn, rvt = *(const u32x4*)gvt, rkr = {0u, 0u, 0u, 0u};
;         if (tid < 256) rkr = *(const u32x4*)gkr;
;         *(LAS u32x4*)(lds + lkn) = rkn; *(LAS u32x2*)(lds + lvt) = (u32x2){rvt.x, rvt.y}; *(LAS u32x2*)(lds + lvt + 16) = (u32x2){rvt.z, rvt.w}; if (tid < 256) *(LAS u32x4*)(lds + lkr) = rkr;
;         rkn = *(const u32x4*)(gkn + 64 * 512); if (tid < 256) rkr = *(const u32x4*)(gkr + 64 * 32);
;         *(LAS u32x4*)(lds + KS_BYTES + lkn) = rkn; if (tid < 256) *(LAS u32x4*)(lds + KS_BYTES + lkr) = rkr;
.LBB0_859:
	s_mul_i32 s14, s21, s33
	s_mul_hi_u32 s15, s21, s64
	s_add_i32 s15, s15, s14
	s_mul_i32 s14, s21, s64
	s_add_u32 s16, s14, s2
	s_addc_u32 s17, s15, s3
	v_cmp_gt_i64_e32 vcc, s[16:17], v[174:175]
	s_mov_b64 s[14:15], -1
	s_cbranch_vccnz .LBB0_858
	s_and_b32 s26, s16, 7
	s_lshr_b64 s[16:17], s[16:17], 3
	s_ashr_i32 s14, s16, 5
	s_lshl_b32 s16, s16, 8
	s_ashr_i32 s15, s14, 31
	s_and_b32 s16, s16, 0x1f00
	s_lshl_b64 s[48:49], s[14:15], 13
	s_add_i32 s16, s16, s24
	s_add_u32 s16, s48, s16
	s_mul_i32 s36, s26, 0xc0
	v_or_b32_e32 v178, s16, v156
	v_lshl_add_u64 v[2:3], v[158:159], 0, s[36:37]
	s_addc_u32 s27, s49, 0
	v_mad_u64_u32 v[2:3], s[16:17], v178, s6, v[2:3]
	v_mad_i32_i24 v3, s27, v196, v3
	v_add_co_u32_e32 v16, vcc, s7, v2
	v_lshl_add_u64 v[24:25], v[2:3], 0, s[40:41]
	s_nop 0
	v_addc_co_u32_e32 v17, vcc, 0, v3, vcc
	global_load_dwordx4 v[4:7], v[2:3], off offset:64
	global_load_dwordx4 v[8:11], v[2:3], off offset:128
	global_load_dwordx4 v[12:15], v[2:3], off
	s_nop 0
	global_load_dwordx4 v[16:19], v[16:17], off
	s_nop 0
	global_load_dwordx4 v[20:23], v[24:25], off offset:64
	s_nop 0
	global_load_dwordx4 v[24:27], v[24:25], off offset:128
	v_lshl_add_u64 v[2:3], s[48:49], 0, v[160:161]
	v_lshlrev_b64 v[2:3], 10, v[2:3]
	v_lshl_add_u64 v[2:3], s[30:31], 0, v[2:3]
	s_lshl_b32 s36, s26, 7
	s_lshl_b32 s25, s26, 6
	v_lshl_add_u64 v[2:3], v[2:3], 0, s[36:37]
	v_mov_b32_e32 v177, v0
	v_lshl_add_u64 v[154:155], v[2:3], 0, v[176:177]
	v_add_u32_e32 v2, s25, v160
	v_ashrrev_i32_e32 v3, 31, v2
	v_lshlrev_b64 v[2:3], 17, v[2:3]
	v_lshl_add_u64 v[2:3], s[34:35], 0, v[2:3]
	s_lshl_b64 s[16:17], s[14:15], 14
	v_lshl_add_u64 v[2:3], v[2:3], 0, s[16:17]
	v_lshl_add_u64 v[152:153], v[2:3], 0, v[176:177]
	global_load_dwordx4 v[32:35], v[154:155], off
	global_load_dwordx4 v[28:31], v[152:153], off
	v_add_co_u32_e32 v40, vcc, 0x10000, v154
	s_nop 1
	v_addc_co_u32_e32 v41, vcc, 0, v155, vcc
	global_load_dwordx4 v[40:43], v[40:41], off
	v_mov_b32_e32 v3, s49
	v_or_b32_e32 v2, s48, v162
	v_lshlrev_b64 v[2:3], 6, v[2:3]
	v_lshl_add_u64 v[180:181], v[164:165], 0, v[2:3]
	s_and_saveexec_b64 s[50:51], s[10:11]
	s_cbranch_execz .Lattn_pro_skip
	v_add_co_u32_e32 v44, vcc, 0x1000, v180
	s_nop 1
	v_addc_co_u32_e32 v45, vcc, 0, v181, vcc
	global_load_dwordx4 v[44:47], v[44:45], off
.Lattn_pro_skip:
	s_or_b64 exec, exec, s[50:51]
	v_mov_b32_e32 v179, s27
	v_add_u32_e32 v177, 0x6000, v198
	s_and_saveexec_b64 s[26:27], s[12:13]
	s_xor_b64 s[50:51], exec, s[26:27]
	s_cbranch_execz .LBB0_862
	s_waitcnt vmcnt(2)
	ds_write_b128 v197, v[32:35]
	s_waitcnt vmcnt(1)
	ds_write2_b64 v177, v[28:29], v[30:31] offset1:32
.LBB0_862:
	s_or_saveexec_b64 s[50:51], s[50:51]
	s_xor_b64 exec, exec, s[50:51]
	s_cbranch_execz .LBB0_864
	global_load_dwordx4 v[36:39], v[180:181], off
	s_waitcnt vmcnt(4)
	ds_write_b128 v197, v[32:35]
	s_waitcnt vmcnt(3)
	ds_write2_b64 v177, v[28:29], v[30:31] offset1:32
	s_waitcnt vmcnt(0)
	ds_write_b128 v199, v[36:39]
.LBB0_864:
	s_or_b64 exec, exec, s[50:51]
	s_and_saveexec_b64 s[26:27], s[12:13]
	s_xor_b64 s[48:49], exec, s[26:27]
	s_cbranch_execz .LBB0_866
	s_waitcnt vmcnt(0)
	ds_write_b128 v197, v[40:43] offset:12288
.LBB0_866:
	s_andn2_saveexec_b64 s[48:49], s[48:49]
	s_cbranch_execz .LBB0_868
	s_waitcnt vmcnt(0)
	ds_write_b128 v197, v[40:43] offset:12288
	ds_write_b128 v199, v[44:47] offset:12288
